# v77 plus hand-written 16x16x32 tile for the QKV v-column tiles: MFMA operands swapped (lane = column), transposed fp16 copy written as 16-byte stores in 64-byte row segments, fp32 new_v as dword store
# speedup vs baseline: 1.0295x; 1.0050x over previous
.LBB0_306:
	s_mul_hi_i32 s24, s82, 0x2aaaaaab
	s_lshr_b32 s25, s24, 31
	s_ashr_i32 s24, s24, 1
	s_add_i32 s28, s24, s25
	s_lshl_b32 s24, s28, 3
	s_or_b32 s29, s24, s83
	v_readlane_b32 s24, v236, 15
	v_readlane_b32 s25, v236, 16
	s_and_b64 s[24:25], s[24:25], exec
	s_cselect_b32 s24, s28, s29
	s_mul_i32 s28, s28, 12
	s_mul_i32 s35, s24, 12
	s_sub_i32 s24, s82, s28
	s_add_i32 s35, s35, s24
	s_mul_hi_i32 s24, s35, 0x2aaaaaab
	s_lshr_b32 s25, s24, 31
	s_ashr_i32 s24, s24, 1
	s_add_i32 s34, s24, s25
	s_mul_i32 s24, s34, 12
	s_sub_i32 s48, s35, s24
	s_lshl_b32 s83, s34, 8
	s_cmp_gt_i32 s48, 7
	s_mov_b64 s[28:29], -1
	s_mulk_i32 s34, 0xc00
	s_cbranch_scc0 .LBB0_448
	s_load_dwordx2 s[30:31], s[22:23], 0xe8
	s_lshl_b32 s46, s48, 8
	s_lshl_b32 s45, s83, 11
	s_add_u32 s24, s62, s45
	s_addc_u32 s25, s63, 0
	s_lshl_b32 s45, s46, 11
	s_add_u32 s28, s64, s45
	s_addc_u32 s29, s65, 0
	s_waitcnt lgkmcnt(0)
	v_readfirstlane_b32 s45, v200
	s_lshr_b32 s45, s45, 6
	s_lshl_b32 s32, s45, 11
	s_add_u32 s32, s32, 16
	s_lshl_b32 s45, s45, 16
	s_add_u32 s24, s24, s45
	s_addc_u32 s25, s25, 0
	s_add_u32 s28, s28, s45
	s_addc_u32 s29, s29, 0
	v_bfe_u32 v173, v200, 4, 2
	v_sub_u32_e32 v173, 0, v173
	v_and_b32_e32 v173, 3, v173
	v_and_b32_e32 v172, 3, v200
	v_xor_b32_e32 v172, v172, v173
	v_bfe_u32 v173, v200, 2, 4
	v_lshlrev_b32_e32 v173, 11, v173
	v_lshl_or_b32 v170, v172, 4, v173
	v_add_u32_e32 v171, 0x8000, v170
	v_bfe_u32 v172, v200, 2, 2
	v_sub_u32_e32 v172, 0, v172
	v_and_b32_e32 v172, 3, v172
	v_bfe_u32 v173, v200, 4, 2
	v_xor_b32_e32 v172, v172, v173
	v_and_b32_e32 v173, 15, v200
	v_bfe_u32 v174, v200, 8, 1
	v_lshl_or_b32 v174, v174, 7, v173
	v_lshlrev_b32_e32 v174, 6, v174
	v_lshl_or_b32 v164, v172, 4, v174
	v_bfe_u32 v174, v200, 6, 2
	v_lshl_or_b32 v174, v174, 6, v173
	v_lshlrev_b32_e32 v174, 6, v174
	v_lshl_or_b32 v165, v172, 4, v174
	v_add_u32_e32 v165, 0x4000, v165
	v_bfe_u32 v172, v200, 6, 2
	v_bfe_u32 v173, v200, 4, 2
	v_lshlrev_b32_e32 v172, 6, v172
	v_lshl_or_b32 v172, v173, 2, v172
	v_add_u32_e32 v172, s46, v172
	v_lshlrev_b32_e32 v172, 2, v172
	v_bfe_u32 v172, v200, 6, 2
	v_and_b32_e32 v173, 15, v200
	v_lshl_or_b32 v172, v172, 6, v173
	v_add_u32_e32 v172, s46, v172
	v_lshlrev_b32_e32 v172, 2, v172
	global_load_dword v132, v172, s[30:31]
	global_load_dword v133, v172, s[30:31] offset:64
	global_load_dword v134, v172, s[30:31] offset:128
	global_load_dword v135, v172, s[30:31] offset:192
	s_mov_b32 s43, s32
	s_mov_b32 m0, s43
	s_nop 0
	global_load_lds_dwordx4 v170, s[24:25]
	s_add_u32 m0, s43, 0x400
	s_nop 0
	global_load_lds_dwordx4 v171, s[24:25]
	s_add_u32 m0, s43, 0x4000
	s_nop 0
	global_load_lds_dwordx4 v170, s[28:29]
	s_add_u32 m0, s43, 0x4400
	s_nop 0
	global_load_lds_dwordx4 v171, s[28:29]
	s_add_u32 s24, s24, 64
	s_addc_u32 s25, s25, 0
	s_add_u32 s28, s28, 64
	s_addc_u32 s29, s29, 0
	s_add_u32 s43, s32, 0x8000
	s_mov_b32 m0, s43
	s_nop 0
	global_load_lds_dwordx4 v170, s[24:25]
	s_add_u32 m0, s43, 0x400
	s_nop 0
	global_load_lds_dwordx4 v171, s[24:25]
	s_add_u32 m0, s43, 0x4000
	s_nop 0
	global_load_lds_dwordx4 v170, s[28:29]
	s_add_u32 m0, s43, 0x4400
	s_nop 0
	global_load_lds_dwordx4 v171, s[28:29]
	s_add_u32 s24, s24, 64
	s_addc_u32 s25, s25, 0
	s_add_u32 s28, s28, 64
	s_addc_u32 s29, s29, 0
	s_add_u32 s43, s32, 0x10000
	s_mov_b32 m0, s43
	s_nop 0
	global_load_lds_dwordx4 v170, s[24:25]
	s_add_u32 m0, s43, 0x400
	s_nop 0
	global_load_lds_dwordx4 v171, s[24:25]
	s_add_u32 m0, s43, 0x4000
	s_nop 0
	global_load_lds_dwordx4 v170, s[28:29]
	s_add_u32 m0, s43, 0x4400
	s_nop 0
	global_load_lds_dwordx4 v171, s[28:29]
	s_add_u32 s24, s24, 64
	s_addc_u32 s25, s25, 0
	s_add_u32 s28, s28, 64
	s_addc_u32 s29, s29, 0
	s_add_u32 s43, s32, 0x18000
	s_mov_b32 m0, s43
	s_nop 0
	global_load_lds_dwordx4 v170, s[24:25]
	s_add_u32 m0, s43, 0x400
	s_nop 0
	global_load_lds_dwordx4 v171, s[24:25]
	s_add_u32 m0, s43, 0x4000
	s_nop 0
	global_load_lds_dwordx4 v170, s[28:29]
	s_add_u32 m0, s43, 0x4400
	s_nop 0
	global_load_lds_dwordx4 v171, s[28:29]
	s_add_u32 s24, s24, 64
	s_addc_u32 s25, s25, 0
	s_add_u32 s28, s28, 64
	s_addc_u32 s29, s29, 0
	s_waitcnt vmcnt(16)
	v_mov_b32_e32 v4, v132
	v_mov_b32_e32 v5, v132
	v_mov_b32_e32 v6, v132
	v_mov_b32_e32 v7, v132
	v_mov_b32_e32 v8, v133
	v_mov_b32_e32 v9, v133
	v_mov_b32_e32 v10, v133
	v_mov_b32_e32 v11, v133
	v_mov_b32_e32 v12, v134
	v_mov_b32_e32 v13, v134
	v_mov_b32_e32 v14, v134
	v_mov_b32_e32 v15, v134
	v_mov_b32_e32 v16, v135
	v_mov_b32_e32 v17, v135
	v_mov_b32_e32 v18, v135
	v_mov_b32_e32 v19, v135
	v_mov_b32_e32 v20, v132
	v_mov_b32_e32 v21, v132
	v_mov_b32_e32 v22, v132
	v_mov_b32_e32 v23, v132
	v_mov_b32_e32 v24, v133
	v_mov_b32_e32 v25, v133
	v_mov_b32_e32 v26, v133
	v_mov_b32_e32 v27, v133
	v_mov_b32_e32 v28, v134
	v_mov_b32_e32 v29, v134
	v_mov_b32_e32 v30, v134
	v_mov_b32_e32 v31, v134
	v_mov_b32_e32 v32, v135
	v_mov_b32_e32 v33, v135
	v_mov_b32_e32 v34, v135
	v_mov_b32_e32 v35, v135
	v_mov_b32_e32 v36, v132
	v_mov_b32_e32 v37, v132
	v_mov_b32_e32 v38, v132
	v_mov_b32_e32 v39, v132
	v_mov_b32_e32 v40, v133
	v_mov_b32_e32 v41, v133
	v_mov_b32_e32 v42, v133
	v_mov_b32_e32 v43, v133
	v_mov_b32_e32 v44, v134
	v_mov_b32_e32 v45, v134
	v_mov_b32_e32 v46, v134
	v_mov_b32_e32 v47, v134
	v_mov_b32_e32 v48, v135
	v_mov_b32_e32 v49, v135
	v_mov_b32_e32 v50, v135
	v_mov_b32_e32 v51, v135
	v_mov_b32_e32 v52, v132
	v_mov_b32_e32 v53, v132
	v_mov_b32_e32 v54, v132
	v_mov_b32_e32 v55, v132
	v_mov_b32_e32 v56, v133
	v_mov_b32_e32 v57, v133
	v_mov_b32_e32 v58, v133
	v_mov_b32_e32 v59, v133
	v_mov_b32_e32 v60, v134
	v_mov_b32_e32 v61, v134
	v_mov_b32_e32 v62, v134
	v_mov_b32_e32 v63, v134
	v_mov_b32_e32 v64, v135
	v_mov_b32_e32 v65, v135
	v_mov_b32_e32 v66, v135
	v_mov_b32_e32 v67, v135
	v_mov_b32_e32 v68, v132
	v_mov_b32_e32 v69, v132
	v_mov_b32_e32 v70, v132
	v_mov_b32_e32 v71, v132
	v_mov_b32_e32 v72, v133
	v_mov_b32_e32 v73, v133
	v_mov_b32_e32 v74, v133
	v_mov_b32_e32 v75, v133
	v_mov_b32_e32 v76, v134
	v_mov_b32_e32 v77, v134
	v_mov_b32_e32 v78, v134
	v_mov_b32_e32 v79, v134
	v_mov_b32_e32 v80, v135
	v_mov_b32_e32 v81, v135
	v_mov_b32_e32 v82, v135
	v_mov_b32_e32 v83, v135
	v_mov_b32_e32 v84, v132
	v_mov_b32_e32 v85, v132
	v_mov_b32_e32 v86, v132
	v_mov_b32_e32 v87, v132
	v_mov_b32_e32 v88, v133
	v_mov_b32_e32 v89, v133
	v_mov_b32_e32 v90, v133
	v_mov_b32_e32 v91, v133
	v_mov_b32_e32 v92, v134
	v_mov_b32_e32 v93, v134
	v_mov_b32_e32 v94, v134
	v_mov_b32_e32 v95, v134
	v_mov_b32_e32 v96, v135
	v_mov_b32_e32 v97, v135
	v_mov_b32_e32 v98, v135
	v_mov_b32_e32 v99, v135
	v_mov_b32_e32 v100, v132
	v_mov_b32_e32 v101, v132
	v_mov_b32_e32 v102, v132
	v_mov_b32_e32 v103, v132
	v_mov_b32_e32 v104, v133
	v_mov_b32_e32 v105, v133
	v_mov_b32_e32 v106, v133
	v_mov_b32_e32 v107, v133
	v_mov_b32_e32 v108, v134
	v_mov_b32_e32 v109, v134
	v_mov_b32_e32 v110, v134
	v_mov_b32_e32 v111, v134
	v_mov_b32_e32 v112, v135
	v_mov_b32_e32 v113, v135
	v_mov_b32_e32 v114, v135
	v_mov_b32_e32 v115, v135
	v_mov_b32_e32 v116, v132
	v_mov_b32_e32 v117, v132
	v_mov_b32_e32 v118, v132
	v_mov_b32_e32 v119, v132
	v_mov_b32_e32 v120, v133
	v_mov_b32_e32 v121, v133
	v_mov_b32_e32 v122, v133
	v_mov_b32_e32 v123, v133
	v_mov_b32_e32 v124, v134
	v_mov_b32_e32 v125, v134
	v_mov_b32_e32 v126, v134
	v_mov_b32_e32 v127, v134
	v_mov_b32_e32 v128, v135
	v_mov_b32_e32 v129, v135
	v_mov_b32_e32 v130, v135
	v_mov_b32_e32 v131, v135
	s_waitcnt vmcnt(12)
	s_barrier
	s_mov_b32 s42, 0
	s_mov_b32 s44, 0
	s_nop 1
	v_add_u32_e32 v168, s42, v165
	v_add_u32_e32 v169, s42, v164
	ds_read_b128 v[132:135], v168 offset:16
	ds_read_b128 v[136:139], v168 offset:1040
	ds_read_b128 v[140:143], v168 offset:2064
	ds_read_b128 v[144:147], v168 offset:3088
	ds_read_b128 v[184:187], v169 offset:16
	ds_read_b128 v[188:191], v169 offset:1040
	ds_read_b128 v[192:195], v169 offset:2064
	ds_read_b128 v[196:199], v169 offset:3088
	s_waitcnt lgkmcnt(0)
.Lt_qkv_v:
	v_add_u32_e32 v169, s42, v164
	v_mfma_f32_16x16x32_f16 v[4:7], v[184:187], v[132:135], v[4:7]
	ds_read_b128 v[238:241], v169 offset:4112
	v_mfma_f32_16x16x32_f16 v[8:11], v[184:187], v[136:139], v[8:11]
	ds_read_b128 v[242:245], v169 offset:5136
	v_mfma_f32_16x16x32_f16 v[12:15], v[184:187], v[140:143], v[12:15]
	ds_read_b128 v[246:249], v169 offset:6160
	v_mfma_f32_16x16x32_f16 v[16:19], v[184:187], v[144:147], v[16:19]
	ds_read_b128 v[250:253], v169 offset:7184
	v_mfma_f32_16x16x32_f16 v[20:23], v[188:191], v[132:135], v[20:23]
	v_mfma_f32_16x16x32_f16 v[24:27], v[188:191], v[136:139], v[24:27]
	v_mfma_f32_16x16x32_f16 v[28:31], v[188:191], v[140:143], v[28:31]
	v_mfma_f32_16x16x32_f16 v[32:35], v[188:191], v[144:147], v[32:35]
	v_mfma_f32_16x16x32_f16 v[36:39], v[192:195], v[132:135], v[36:39]
	v_mfma_f32_16x16x32_f16 v[40:43], v[192:195], v[136:139], v[40:43]
	v_mfma_f32_16x16x32_f16 v[44:47], v[192:195], v[140:143], v[44:47]
	v_mfma_f32_16x16x32_f16 v[48:51], v[192:195], v[144:147], v[48:51]
	v_mfma_f32_16x16x32_f16 v[52:55], v[196:199], v[132:135], v[52:55]
	v_mfma_f32_16x16x32_f16 v[56:59], v[196:199], v[136:139], v[56:59]
	v_mfma_f32_16x16x32_f16 v[60:63], v[196:199], v[140:143], v[60:63]
	v_mfma_f32_16x16x32_f16 v[64:67], v[196:199], v[144:147], v[64:67]
	s_waitcnt vmcnt(8) lgkmcnt(0)
	s_barrier
	s_add_i32 s43, s42, 0x8000
	s_cmp_lg_u32 s42, 0x18000
	s_cselect_b32 s43, s43, 0
	v_add_u32_e32 v168, s43, v165
	v_add_u32_e32 v169, s43, v164
	s_add_u32 vcc_lo, s32, s42
	v_mfma_f32_16x16x32_f16 v[68:71], v[238:241], v[132:135], v[68:71]
	ds_read_b128 v[148:151], v168 offset:16
	ds_read_b128 v[184:187], v169 offset:16
	v_mfma_f32_16x16x32_f16 v[72:75], v[238:241], v[136:139], v[72:75]
	ds_read_b128 v[152:155], v168 offset:1040
	ds_read_b128 v[188:191], v169 offset:1040
	v_mfma_f32_16x16x32_f16 v[76:79], v[238:241], v[140:143], v[76:79]
	ds_read_b128 v[156:159], v168 offset:2064
	ds_read_b128 v[192:195], v169 offset:2064
	v_mfma_f32_16x16x32_f16 v[80:83], v[238:241], v[144:147], v[80:83]
	ds_read_b128 v[160:163], v168 offset:3088
	ds_read_b128 v[196:199], v169 offset:3088
	v_mfma_f32_16x16x32_f16 v[84:87], v[242:245], v[132:135], v[84:87]
	v_mfma_f32_16x16x32_f16 v[88:91], v[242:245], v[136:139], v[88:91]
	v_mfma_f32_16x16x32_f16 v[92:95], v[242:245], v[140:143], v[92:95]
	v_mfma_f32_16x16x32_f16 v[96:99], v[242:245], v[144:147], v[96:99]
	v_mfma_f32_16x16x32_f16 v[100:103], v[246:249], v[132:135], v[100:103]
	s_mov_b32 m0, vcc_lo
	s_nop 0
	global_load_lds_dwordx4 v170, s[24:25]
	v_mfma_f32_16x16x32_f16 v[104:107], v[246:249], v[136:139], v[104:107]
	s_add_u32 m0, vcc_lo, 0x400
	s_nop 0
	global_load_lds_dwordx4 v171, s[24:25]
	v_mfma_f32_16x16x32_f16 v[108:111], v[246:249], v[140:143], v[108:111]
	s_add_u32 m0, vcc_lo, 0x4000
	s_nop 0
	global_load_lds_dwordx4 v170, s[28:29]
	v_mfma_f32_16x16x32_f16 v[112:115], v[246:249], v[144:147], v[112:115]
	s_add_u32 m0, vcc_lo, 0x4400
	s_nop 0
	global_load_lds_dwordx4 v171, s[28:29]
	v_mfma_f32_16x16x32_f16 v[116:119], v[250:253], v[132:135], v[116:119]
	v_mfma_f32_16x16x32_f16 v[120:123], v[250:253], v[136:139], v[120:123]
	v_mfma_f32_16x16x32_f16 v[124:127], v[250:253], v[140:143], v[124:127]
	v_mfma_f32_16x16x32_f16 v[128:131], v[250:253], v[144:147], v[128:131]
	s_waitcnt lgkmcnt(0)
	s_mov_b32 s42, s43
	s_add_u32 s24, s24, 64
	s_addc_u32 s25, s25, 0
	s_add_u32 s28, s28, 64
	s_addc_u32 s29, s29, 0
	v_add_u32_e32 v169, s42, v164
	v_mfma_f32_16x16x32_f16 v[4:7], v[184:187], v[148:151], v[4:7]
	ds_read_b128 v[238:241], v169 offset:4112
	v_mfma_f32_16x16x32_f16 v[8:11], v[184:187], v[152:155], v[8:11]
	ds_read_b128 v[242:245], v169 offset:5136
	v_mfma_f32_16x16x32_f16 v[12:15], v[184:187], v[156:159], v[12:15]
	ds_read_b128 v[246:249], v169 offset:6160
	v_mfma_f32_16x16x32_f16 v[16:19], v[184:187], v[160:163], v[16:19]
	ds_read_b128 v[250:253], v169 offset:7184
	v_mfma_f32_16x16x32_f16 v[20:23], v[188:191], v[148:151], v[20:23]
	v_mfma_f32_16x16x32_f16 v[24:27], v[188:191], v[152:155], v[24:27]
	v_mfma_f32_16x16x32_f16 v[28:31], v[188:191], v[156:159], v[28:31]
	v_mfma_f32_16x16x32_f16 v[32:35], v[188:191], v[160:163], v[32:35]
	v_mfma_f32_16x16x32_f16 v[36:39], v[192:195], v[148:151], v[36:39]
	v_mfma_f32_16x16x32_f16 v[40:43], v[192:195], v[152:155], v[40:43]
	v_mfma_f32_16x16x32_f16 v[44:47], v[192:195], v[156:159], v[44:47]
	v_mfma_f32_16x16x32_f16 v[48:51], v[192:195], v[160:163], v[48:51]
	v_mfma_f32_16x16x32_f16 v[52:55], v[196:199], v[148:151], v[52:55]
	v_mfma_f32_16x16x32_f16 v[56:59], v[196:199], v[152:155], v[56:59]
	v_mfma_f32_16x16x32_f16 v[60:63], v[196:199], v[156:159], v[60:63]
	v_mfma_f32_16x16x32_f16 v[64:67], v[196:199], v[160:163], v[64:67]
	s_waitcnt vmcnt(8) lgkmcnt(0)
	s_barrier
	s_add_i32 s43, s42, 0x8000
	s_cmp_lg_u32 s42, 0x18000
	s_cselect_b32 s43, s43, 0
	v_add_u32_e32 v168, s43, v165
	v_add_u32_e32 v169, s43, v164
	s_add_u32 vcc_lo, s32, s42
	v_mfma_f32_16x16x32_f16 v[68:71], v[238:241], v[148:151], v[68:71]
	ds_read_b128 v[132:135], v168 offset:16
	ds_read_b128 v[184:187], v169 offset:16
	v_mfma_f32_16x16x32_f16 v[72:75], v[238:241], v[152:155], v[72:75]
	ds_read_b128 v[136:139], v168 offset:1040
	ds_read_b128 v[188:191], v169 offset:1040
	v_mfma_f32_16x16x32_f16 v[76:79], v[238:241], v[156:159], v[76:79]
	ds_read_b128 v[140:143], v168 offset:2064
	ds_read_b128 v[192:195], v169 offset:2064
	v_mfma_f32_16x16x32_f16 v[80:83], v[238:241], v[160:163], v[80:83]
	ds_read_b128 v[144:147], v168 offset:3088
	ds_read_b128 v[196:199], v169 offset:3088
	v_mfma_f32_16x16x32_f16 v[84:87], v[242:245], v[148:151], v[84:87]
	v_mfma_f32_16x16x32_f16 v[88:91], v[242:245], v[152:155], v[88:91]
	v_mfma_f32_16x16x32_f16 v[92:95], v[242:245], v[156:159], v[92:95]
	v_mfma_f32_16x16x32_f16 v[96:99], v[242:245], v[160:163], v[96:99]
	v_mfma_f32_16x16x32_f16 v[100:103], v[246:249], v[148:151], v[100:103]
	s_mov_b32 m0, vcc_lo
	s_nop 0
	global_load_lds_dwordx4 v170, s[24:25]
	v_mfma_f32_16x16x32_f16 v[104:107], v[246:249], v[152:155], v[104:107]
	s_add_u32 m0, vcc_lo, 0x400
	s_nop 0
	global_load_lds_dwordx4 v171, s[24:25]
	v_mfma_f32_16x16x32_f16 v[108:111], v[246:249], v[156:159], v[108:111]
	s_add_u32 m0, vcc_lo, 0x4000
	s_nop 0
	global_load_lds_dwordx4 v170, s[28:29]
	v_mfma_f32_16x16x32_f16 v[112:115], v[246:249], v[160:163], v[112:115]
	s_add_u32 m0, vcc_lo, 0x4400
	s_nop 0
	global_load_lds_dwordx4 v171, s[28:29]
	v_mfma_f32_16x16x32_f16 v[116:119], v[250:253], v[148:151], v[116:119]
	v_mfma_f32_16x16x32_f16 v[120:123], v[250:253], v[152:155], v[120:123]
	v_mfma_f32_16x16x32_f16 v[124:127], v[250:253], v[156:159], v[124:127]
	v_mfma_f32_16x16x32_f16 v[128:131], v[250:253], v[160:163], v[128:131]
	s_waitcnt lgkmcnt(0)
	s_mov_b32 s42, s43
	s_add_u32 s24, s24, 64
	s_addc_u32 s25, s25, 0
	s_add_u32 s28, s28, 64
	s_addc_u32 s29, s29, 0
	s_add_i32 s44, s44, 2
	s_cmp_lt_u32 s44, 28
	s_cbranch_scc1 .Lt_qkv_v
	v_add_u32_e32 v169, s42, v164
	v_mfma_f32_16x16x32_f16 v[4:7], v[184:187], v[132:135], v[4:7]
	ds_read_b128 v[238:241], v169 offset:4112
	v_mfma_f32_16x16x32_f16 v[8:11], v[184:187], v[136:139], v[8:11]
	ds_read_b128 v[242:245], v169 offset:5136
	v_mfma_f32_16x16x32_f16 v[12:15], v[184:187], v[140:143], v[12:15]
	ds_read_b128 v[246:249], v169 offset:6160
	v_mfma_f32_16x16x32_f16 v[16:19], v[184:187], v[144:147], v[16:19]
	ds_read_b128 v[250:253], v169 offset:7184
	v_mfma_f32_16x16x32_f16 v[20:23], v[188:191], v[132:135], v[20:23]
	v_mfma_f32_16x16x32_f16 v[24:27], v[188:191], v[136:139], v[24:27]
	v_mfma_f32_16x16x32_f16 v[28:31], v[188:191], v[140:143], v[28:31]
	v_mfma_f32_16x16x32_f16 v[32:35], v[188:191], v[144:147], v[32:35]
	v_mfma_f32_16x16x32_f16 v[36:39], v[192:195], v[132:135], v[36:39]
	v_mfma_f32_16x16x32_f16 v[40:43], v[192:195], v[136:139], v[40:43]
	v_mfma_f32_16x16x32_f16 v[44:47], v[192:195], v[140:143], v[44:47]
	v_mfma_f32_16x16x32_f16 v[48:51], v[192:195], v[144:147], v[48:51]
	v_mfma_f32_16x16x32_f16 v[52:55], v[196:199], v[132:135], v[52:55]
	v_mfma_f32_16x16x32_f16 v[56:59], v[196:199], v[136:139], v[56:59]
	v_mfma_f32_16x16x32_f16 v[60:63], v[196:199], v[140:143], v[60:63]
	v_mfma_f32_16x16x32_f16 v[64:67], v[196:199], v[144:147], v[64:67]
	s_waitcnt vmcnt(8) lgkmcnt(0)
	s_barrier
	s_add_i32 s43, s42, 0x8000
	s_cmp_lg_u32 s42, 0x18000
	s_cselect_b32 s43, s43, 0
	v_add_u32_e32 v168, s43, v165
	v_add_u32_e32 v169, s43, v164
	v_mfma_f32_16x16x32_f16 v[68:71], v[238:241], v[132:135], v[68:71]
	ds_read_b128 v[148:151], v168 offset:16
	ds_read_b128 v[184:187], v169 offset:16
	v_mfma_f32_16x16x32_f16 v[72:75], v[238:241], v[136:139], v[72:75]
	ds_read_b128 v[152:155], v168 offset:1040
	ds_read_b128 v[188:191], v169 offset:1040
	v_mfma_f32_16x16x32_f16 v[76:79], v[238:241], v[140:143], v[76:79]
	ds_read_b128 v[156:159], v168 offset:2064
	ds_read_b128 v[192:195], v169 offset:2064
	v_mfma_f32_16x16x32_f16 v[80:83], v[238:241], v[144:147], v[80:83]
	ds_read_b128 v[160:163], v168 offset:3088
	ds_read_b128 v[196:199], v169 offset:3088
	v_mfma_f32_16x16x32_f16 v[84:87], v[242:245], v[132:135], v[84:87]
	v_mfma_f32_16x16x32_f16 v[88:91], v[242:245], v[136:139], v[88:91]
	v_mfma_f32_16x16x32_f16 v[92:95], v[242:245], v[140:143], v[92:95]
	v_mfma_f32_16x16x32_f16 v[96:99], v[242:245], v[144:147], v[96:99]
	v_mfma_f32_16x16x32_f16 v[100:103], v[246:249], v[132:135], v[100:103]
	v_mfma_f32_16x16x32_f16 v[104:107], v[246:249], v[136:139], v[104:107]
	v_mfma_f32_16x16x32_f16 v[108:111], v[246:249], v[140:143], v[108:111]
	v_mfma_f32_16x16x32_f16 v[112:115], v[246:249], v[144:147], v[112:115]
	v_mfma_f32_16x16x32_f16 v[116:119], v[250:253], v[132:135], v[116:119]
	v_mfma_f32_16x16x32_f16 v[120:123], v[250:253], v[136:139], v[120:123]
	v_mfma_f32_16x16x32_f16 v[124:127], v[250:253], v[140:143], v[124:127]
	v_mfma_f32_16x16x32_f16 v[128:131], v[250:253], v[144:147], v[128:131]
	s_waitcnt lgkmcnt(0)
	s_mov_b32 s42, s43
	v_add_u32_e32 v169, s42, v164
	v_mfma_f32_16x16x32_f16 v[4:7], v[184:187], v[148:151], v[4:7]
	ds_read_b128 v[238:241], v169 offset:4112
	v_mfma_f32_16x16x32_f16 v[8:11], v[184:187], v[152:155], v[8:11]
	ds_read_b128 v[242:245], v169 offset:5136
	v_mfma_f32_16x16x32_f16 v[12:15], v[184:187], v[156:159], v[12:15]
	ds_read_b128 v[246:249], v169 offset:6160
	v_mfma_f32_16x16x32_f16 v[16:19], v[184:187], v[160:163], v[16:19]
	ds_read_b128 v[250:253], v169 offset:7184
	v_mfma_f32_16x16x32_f16 v[20:23], v[188:191], v[148:151], v[20:23]
	v_mfma_f32_16x16x32_f16 v[24:27], v[188:191], v[152:155], v[24:27]
	v_mfma_f32_16x16x32_f16 v[28:31], v[188:191], v[156:159], v[28:31]
	v_mfma_f32_16x16x32_f16 v[32:35], v[188:191], v[160:163], v[32:35]
	v_mfma_f32_16x16x32_f16 v[36:39], v[192:195], v[148:151], v[36:39]
	v_mfma_f32_16x16x32_f16 v[40:43], v[192:195], v[152:155], v[40:43]
	v_mfma_f32_16x16x32_f16 v[44:47], v[192:195], v[156:159], v[44:47]
	v_mfma_f32_16x16x32_f16 v[48:51], v[192:195], v[160:163], v[48:51]
	v_mfma_f32_16x16x32_f16 v[52:55], v[196:199], v[148:151], v[52:55]
	v_mfma_f32_16x16x32_f16 v[56:59], v[196:199], v[152:155], v[56:59]
	v_mfma_f32_16x16x32_f16 v[60:63], v[196:199], v[156:159], v[60:63]
	v_mfma_f32_16x16x32_f16 v[64:67], v[196:199], v[160:163], v[64:67]
	s_waitcnt vmcnt(4) lgkmcnt(0)
	s_barrier
	s_add_i32 s43, s42, 0x8000
	s_cmp_lg_u32 s42, 0x18000
	s_cselect_b32 s43, s43, 0
	v_add_u32_e32 v168, s43, v165
	v_add_u32_e32 v169, s43, v164
	v_mfma_f32_16x16x32_f16 v[68:71], v[238:241], v[148:151], v[68:71]
	ds_read_b128 v[132:135], v168 offset:16
	ds_read_b128 v[184:187], v169 offset:16
	v_mfma_f32_16x16x32_f16 v[72:75], v[238:241], v[152:155], v[72:75]
	ds_read_b128 v[136:139], v168 offset:1040
	ds_read_b128 v[188:191], v169 offset:1040
	v_mfma_f32_16x16x32_f16 v[76:79], v[238:241], v[156:159], v[76:79]
	ds_read_b128 v[140:143], v168 offset:2064
	ds_read_b128 v[192:195], v169 offset:2064
	v_mfma_f32_16x16x32_f16 v[80:83], v[238:241], v[160:163], v[80:83]
	ds_read_b128 v[144:147], v168 offset:3088
	ds_read_b128 v[196:199], v169 offset:3088
	v_mfma_f32_16x16x32_f16 v[84:87], v[242:245], v[148:151], v[84:87]
	v_mfma_f32_16x16x32_f16 v[88:91], v[242:245], v[152:155], v[88:91]
	v_mfma_f32_16x16x32_f16 v[92:95], v[242:245], v[156:159], v[92:95]
	v_mfma_f32_16x16x32_f16 v[96:99], v[242:245], v[160:163], v[96:99]
	v_mfma_f32_16x16x32_f16 v[100:103], v[246:249], v[148:151], v[100:103]
	v_mfma_f32_16x16x32_f16 v[104:107], v[246:249], v[152:155], v[104:107]
	v_mfma_f32_16x16x32_f16 v[108:111], v[246:249], v[156:159], v[108:111]
	v_mfma_f32_16x16x32_f16 v[112:115], v[246:249], v[160:163], v[112:115]
	v_mfma_f32_16x16x32_f16 v[116:119], v[250:253], v[148:151], v[116:119]
	v_mfma_f32_16x16x32_f16 v[120:123], v[250:253], v[152:155], v[120:123]
	v_mfma_f32_16x16x32_f16 v[124:127], v[250:253], v[156:159], v[124:127]
	v_mfma_f32_16x16x32_f16 v[128:131], v[250:253], v[160:163], v[128:131]
	s_waitcnt lgkmcnt(0)
	s_mov_b32 s42, s43
	v_add_u32_e32 v169, s42, v164
	v_mfma_f32_16x16x32_f16 v[4:7], v[184:187], v[132:135], v[4:7]
	ds_read_b128 v[238:241], v169 offset:4112
	v_mfma_f32_16x16x32_f16 v[8:11], v[184:187], v[136:139], v[8:11]
	ds_read_b128 v[242:245], v169 offset:5136
	v_mfma_f32_16x16x32_f16 v[12:15], v[184:187], v[140:143], v[12:15]
	ds_read_b128 v[246:249], v169 offset:6160
	v_mfma_f32_16x16x32_f16 v[16:19], v[184:187], v[144:147], v[16:19]
	ds_read_b128 v[250:253], v169 offset:7184
	v_mfma_f32_16x16x32_f16 v[20:23], v[188:191], v[132:135], v[20:23]
	v_mfma_f32_16x16x32_f16 v[24:27], v[188:191], v[136:139], v[24:27]
	v_mfma_f32_16x16x32_f16 v[28:31], v[188:191], v[140:143], v[28:31]
	v_mfma_f32_16x16x32_f16 v[32:35], v[188:191], v[144:147], v[32:35]
	v_mfma_f32_16x16x32_f16 v[36:39], v[192:195], v[132:135], v[36:39]
	v_mfma_f32_16x16x32_f16 v[40:43], v[192:195], v[136:139], v[40:43]
	v_mfma_f32_16x16x32_f16 v[44:47], v[192:195], v[140:143], v[44:47]
	v_mfma_f32_16x16x32_f16 v[48:51], v[192:195], v[144:147], v[48:51]
	v_mfma_f32_16x16x32_f16 v[52:55], v[196:199], v[132:135], v[52:55]
	v_mfma_f32_16x16x32_f16 v[56:59], v[196:199], v[136:139], v[56:59]
	v_mfma_f32_16x16x32_f16 v[60:63], v[196:199], v[140:143], v[60:63]
	v_mfma_f32_16x16x32_f16 v[64:67], v[196:199], v[144:147], v[64:67]
	s_waitcnt vmcnt(0) lgkmcnt(0)
	s_barrier
	s_add_i32 s43, s42, 0x8000
	s_cmp_lg_u32 s42, 0x18000
	s_cselect_b32 s43, s43, 0
	v_add_u32_e32 v168, s43, v165
	v_add_u32_e32 v169, s43, v164
	v_mfma_f32_16x16x32_f16 v[68:71], v[238:241], v[132:135], v[68:71]
	ds_read_b128 v[148:151], v168 offset:16
	ds_read_b128 v[184:187], v169 offset:16
	v_mfma_f32_16x16x32_f16 v[72:75], v[238:241], v[136:139], v[72:75]
	ds_read_b128 v[152:155], v168 offset:1040
	ds_read_b128 v[188:191], v169 offset:1040
	v_mfma_f32_16x16x32_f16 v[76:79], v[238:241], v[140:143], v[76:79]
	ds_read_b128 v[156:159], v168 offset:2064
	ds_read_b128 v[192:195], v169 offset:2064
	v_mfma_f32_16x16x32_f16 v[80:83], v[238:241], v[144:147], v[80:83]
	ds_read_b128 v[160:163], v168 offset:3088
	ds_read_b128 v[196:199], v169 offset:3088
	v_mfma_f32_16x16x32_f16 v[84:87], v[242:245], v[132:135], v[84:87]
	v_mfma_f32_16x16x32_f16 v[88:91], v[242:245], v[136:139], v[88:91]
	v_mfma_f32_16x16x32_f16 v[92:95], v[242:245], v[140:143], v[92:95]
	v_mfma_f32_16x16x32_f16 v[96:99], v[242:245], v[144:147], v[96:99]
	v_mfma_f32_16x16x32_f16 v[100:103], v[246:249], v[132:135], v[100:103]
	v_mfma_f32_16x16x32_f16 v[104:107], v[246:249], v[136:139], v[104:107]
	v_mfma_f32_16x16x32_f16 v[108:111], v[246:249], v[140:143], v[108:111]
	v_mfma_f32_16x16x32_f16 v[112:115], v[246:249], v[144:147], v[112:115]
	v_mfma_f32_16x16x32_f16 v[116:119], v[250:253], v[132:135], v[116:119]
	v_mfma_f32_16x16x32_f16 v[120:123], v[250:253], v[136:139], v[120:123]
	v_mfma_f32_16x16x32_f16 v[124:127], v[250:253], v[140:143], v[124:127]
	v_mfma_f32_16x16x32_f16 v[128:131], v[250:253], v[144:147], v[128:131]
	s_waitcnt lgkmcnt(0)
	s_mov_b32 s42, s43
	v_add_u32_e32 v169, s42, v164
	v_mfma_f32_16x16x32_f16 v[4:7], v[184:187], v[148:151], v[4:7]
	ds_read_b128 v[238:241], v169 offset:4112
	v_mfma_f32_16x16x32_f16 v[8:11], v[184:187], v[152:155], v[8:11]
	ds_read_b128 v[242:245], v169 offset:5136
	v_mfma_f32_16x16x32_f16 v[12:15], v[184:187], v[156:159], v[12:15]
	ds_read_b128 v[246:249], v169 offset:6160
	v_mfma_f32_16x16x32_f16 v[16:19], v[184:187], v[160:163], v[16:19]
	ds_read_b128 v[250:253], v169 offset:7184
	v_mfma_f32_16x16x32_f16 v[20:23], v[188:191], v[148:151], v[20:23]
	v_mfma_f32_16x16x32_f16 v[24:27], v[188:191], v[152:155], v[24:27]
	v_mfma_f32_16x16x32_f16 v[28:31], v[188:191], v[156:159], v[28:31]
	v_mfma_f32_16x16x32_f16 v[32:35], v[188:191], v[160:163], v[32:35]
	v_mfma_f32_16x16x32_f16 v[36:39], v[192:195], v[148:151], v[36:39]
	v_mfma_f32_16x16x32_f16 v[40:43], v[192:195], v[152:155], v[40:43]
	v_mfma_f32_16x16x32_f16 v[44:47], v[192:195], v[156:159], v[44:47]
	v_mfma_f32_16x16x32_f16 v[48:51], v[192:195], v[160:163], v[48:51]
	v_mfma_f32_16x16x32_f16 v[52:55], v[196:199], v[148:151], v[52:55]
	v_mfma_f32_16x16x32_f16 v[56:59], v[196:199], v[152:155], v[56:59]
	v_mfma_f32_16x16x32_f16 v[60:63], v[196:199], v[156:159], v[60:63]
	v_mfma_f32_16x16x32_f16 v[64:67], v[196:199], v[160:163], v[64:67]
	s_waitcnt lgkmcnt(0)
	s_barrier
	v_mfma_f32_16x16x32_f16 v[68:71], v[238:241], v[148:151], v[68:71]
	v_mfma_f32_16x16x32_f16 v[72:75], v[238:241], v[152:155], v[72:75]
	v_mfma_f32_16x16x32_f16 v[76:79], v[238:241], v[156:159], v[76:79]
	v_mfma_f32_16x16x32_f16 v[80:83], v[238:241], v[160:163], v[80:83]
	v_mfma_f32_16x16x32_f16 v[84:87], v[242:245], v[148:151], v[84:87]
	v_mfma_f32_16x16x32_f16 v[88:91], v[242:245], v[152:155], v[88:91]
	v_mfma_f32_16x16x32_f16 v[92:95], v[242:245], v[156:159], v[92:95]
	v_mfma_f32_16x16x32_f16 v[96:99], v[242:245], v[160:163], v[96:99]
	v_mfma_f32_16x16x32_f16 v[100:103], v[246:249], v[148:151], v[100:103]
	v_mfma_f32_16x16x32_f16 v[104:107], v[246:249], v[152:155], v[104:107]
	v_mfma_f32_16x16x32_f16 v[108:111], v[246:249], v[156:159], v[108:111]
	v_mfma_f32_16x16x32_f16 v[112:115], v[246:249], v[160:163], v[112:115]
	v_mfma_f32_16x16x32_f16 v[116:119], v[250:253], v[148:151], v[116:119]
	v_mfma_f32_16x16x32_f16 v[120:123], v[250:253], v[152:155], v[120:123]
	v_mfma_f32_16x16x32_f16 v[124:127], v[250:253], v[156:159], v[124:127]
	v_mfma_f32_16x16x32_f16 v[128:131], v[250:253], v[160:163], v[128:131]
	s_sub_i32 s43, s48, 8
	s_lshl_b32 s43, s43, 2
	s_cmp_lt_u32 s83, 0x1000
	s_cbranch_scc0 .Lqv_lat
	s_lshr_b32 s44, s83, 4
	s_add_u32 s44, s44, s43
	s_lshl_b32 s42, s44, 16
	s_add_u32 s28, s70, s42
	s_addc_u32 s29, s71, 0
	s_lshl_b32 s44, s44, 15
	s_add_u32 s24, s58, s44
	s_addc_u32 s25, s59, 0
	s_mov_b32 s32, 9
	s_branch .Lqv_addr
.Lqv_lat:
	s_sub_u32 s44, s83, 0x1000
	s_lshr_b32 s42, s44, 12
	s_lshl_b32 s42, s42, 4
	s_add_u32 s42, s42, s43
	s_lshl_b32 s42, s42, 19
	s_and_b32 s44, s44, 0xfff
	s_lshl_b32 s44, s44, 1
	s_add_u32 s42, s42, s44
	s_add_u32 s24, s68, s42
	s_addc_u32 s25, s69, 0
	s_mov_b32 s32, 13
.Lqv_addr:
	s_lshl_b32 s42, 16, s32
	v_and_b32_e32 v172, 15, v200
	v_bfe_u32 v173, v200, 4, 2
	v_bfe_u32 v174, v200, 6, 2
	v_bfe_u32 v175, v200, 8, 1
	v_lshl_or_b32 v174, v174, 6, v172
	v_lshl_or_b32 v175, v175, 5, v173
	v_lshlrev_b32_e32 v177, s32, v174
	v_lshl_add_u32 v177, v175, 3, v177
	v_and_b32_e32 v172, 1, v173
	v_mul_u32_u24_e32 v172, 24, v172
	v_add_u32_e32 v177, v177, v172
	v_and_b32_e32 v172, 15, v200
	v_bfe_u32 v174, v200, 6, 2
	v_lshlrev_b32_e32 v176, 16, v174
	v_lshl_add_u32 v176, v175, 10, v176
	v_lshl_add_u32 v176, v172, 2, v176
	v_cvt_pk_f16_f32 v172, v4, v5
	v_cvt_pk_f16_f32 v173, v6, v7
	v_cvt_pk_f16_f32 v174, v20, v21
	v_cvt_pk_f16_f32 v175, v22, v23
	s_nop 1
	v_permlane16_swap_b32_e32 v172, v174
	v_permlane16_swap_b32_e32 v173, v175
	global_store_dwordx4 v177, v[172:175], s[24:25]
	v_cvt_pk_f16_f32 v228, v36, v37
	v_cvt_pk_f16_f32 v229, v38, v39
	v_cvt_pk_f16_f32 v230, v52, v53
	v_cvt_pk_f16_f32 v231, v54, v55
	s_nop 1
	v_permlane16_swap_b32_e32 v228, v230
	v_permlane16_swap_b32_e32 v229, v231
	global_store_dwordx4 v177, v[228:231], s[24:25] offset:64
	v_cvt_pk_f16_f32 v172, v68, v69
	v_cvt_pk_f16_f32 v173, v70, v71
	v_cvt_pk_f16_f32 v174, v84, v85
	v_cvt_pk_f16_f32 v175, v86, v87
	s_nop 1
	v_permlane16_swap_b32_e32 v172, v174
	v_permlane16_swap_b32_e32 v173, v175
	global_store_dwordx4 v177, v[172:175], s[24:25] offset:128
	v_cvt_pk_f16_f32 v228, v100, v101
	v_cvt_pk_f16_f32 v229, v102, v103
	v_cvt_pk_f16_f32 v230, v116, v117
	v_cvt_pk_f16_f32 v231, v118, v119
	s_nop 1
	v_permlane16_swap_b32_e32 v228, v230
	v_permlane16_swap_b32_e32 v229, v231
	global_store_dwordx4 v177, v[228:231], s[24:25] offset:192
	v_add_u32_e32 v177, s42, v177
	v_cvt_pk_f16_f32 v172, v8, v9
	v_cvt_pk_f16_f32 v173, v10, v11
	v_cvt_pk_f16_f32 v174, v24, v25
	v_cvt_pk_f16_f32 v175, v26, v27
	s_nop 1
	v_permlane16_swap_b32_e32 v172, v174
	v_permlane16_swap_b32_e32 v173, v175
	global_store_dwordx4 v177, v[172:175], s[24:25]
	v_cvt_pk_f16_f32 v228, v40, v41
	v_cvt_pk_f16_f32 v229, v42, v43
	v_cvt_pk_f16_f32 v230, v56, v57
	v_cvt_pk_f16_f32 v231, v58, v59
	s_nop 1
	v_permlane16_swap_b32_e32 v228, v230
	v_permlane16_swap_b32_e32 v229, v231
	global_store_dwordx4 v177, v[228:231], s[24:25] offset:64
	v_cvt_pk_f16_f32 v172, v72, v73
	v_cvt_pk_f16_f32 v173, v74, v75
	v_cvt_pk_f16_f32 v174, v88, v89
	v_cvt_pk_f16_f32 v175, v90, v91
	s_nop 1
	v_permlane16_swap_b32_e32 v172, v174
	v_permlane16_swap_b32_e32 v173, v175
	global_store_dwordx4 v177, v[172:175], s[24:25] offset:128
	v_cvt_pk_f16_f32 v228, v104, v105
	v_cvt_pk_f16_f32 v229, v106, v107
	v_cvt_pk_f16_f32 v230, v120, v121
	v_cvt_pk_f16_f32 v231, v122, v123
	s_nop 1
	v_permlane16_swap_b32_e32 v228, v230
	v_permlane16_swap_b32_e32 v229, v231
	global_store_dwordx4 v177, v[228:231], s[24:25] offset:192
	v_add_u32_e32 v177, s42, v177
	v_cvt_pk_f16_f32 v172, v12, v13
	v_cvt_pk_f16_f32 v173, v14, v15
	v_cvt_pk_f16_f32 v174, v28, v29
	v_cvt_pk_f16_f32 v175, v30, v31
	s_nop 1
	v_permlane16_swap_b32_e32 v172, v174
	v_permlane16_swap_b32_e32 v173, v175
	global_store_dwordx4 v177, v[172:175], s[24:25]
	v_cvt_pk_f16_f32 v228, v44, v45
	v_cvt_pk_f16_f32 v229, v46, v47
	v_cvt_pk_f16_f32 v230, v60, v61
	v_cvt_pk_f16_f32 v231, v62, v63
	s_nop 1
	v_permlane16_swap_b32_e32 v228, v230
	v_permlane16_swap_b32_e32 v229, v231
	global_store_dwordx4 v177, v[228:231], s[24:25] offset:64
	v_cvt_pk_f16_f32 v172, v76, v77
	v_cvt_pk_f16_f32 v173, v78, v79
	v_cvt_pk_f16_f32 v174, v92, v93
	v_cvt_pk_f16_f32 v175, v94, v95
	s_nop 1
	v_permlane16_swap_b32_e32 v172, v174
	v_permlane16_swap_b32_e32 v173, v175
	global_store_dwordx4 v177, v[172:175], s[24:25] offset:128
	v_cvt_pk_f16_f32 v228, v108, v109
	v_cvt_pk_f16_f32 v229, v110, v111
	v_cvt_pk_f16_f32 v230, v124, v125
	v_cvt_pk_f16_f32 v231, v126, v127
	s_nop 1
	v_permlane16_swap_b32_e32 v228, v230
	v_permlane16_swap_b32_e32 v229, v231
	global_store_dwordx4 v177, v[228:231], s[24:25] offset:192
	v_add_u32_e32 v177, s42, v177
	v_cvt_pk_f16_f32 v172, v16, v17
	v_cvt_pk_f16_f32 v173, v18, v19
	v_cvt_pk_f16_f32 v174, v32, v33
	v_cvt_pk_f16_f32 v175, v34, v35
	s_nop 1
	v_permlane16_swap_b32_e32 v172, v174
	v_permlane16_swap_b32_e32 v173, v175
	global_store_dwordx4 v177, v[172:175], s[24:25]
	v_cvt_pk_f16_f32 v228, v48, v49
	v_cvt_pk_f16_f32 v229, v50, v51
	v_cvt_pk_f16_f32 v230, v64, v65
	v_cvt_pk_f16_f32 v231, v66, v67
	s_nop 1
	v_permlane16_swap_b32_e32 v228, v230
	v_permlane16_swap_b32_e32 v229, v231
	global_store_dwordx4 v177, v[228:231], s[24:25] offset:64
	v_cvt_pk_f16_f32 v172, v80, v81
	v_cvt_pk_f16_f32 v173, v82, v83
	v_cvt_pk_f16_f32 v174, v96, v97
	v_cvt_pk_f16_f32 v175, v98, v99
	s_nop 1
	v_permlane16_swap_b32_e32 v172, v174
	v_permlane16_swap_b32_e32 v173, v175
	global_store_dwordx4 v177, v[172:175], s[24:25] offset:128
	v_cvt_pk_f16_f32 v228, v112, v113
	v_cvt_pk_f16_f32 v229, v114, v115
	v_cvt_pk_f16_f32 v230, v128, v129
	v_cvt_pk_f16_f32 v231, v130, v131
	s_nop 1
	v_permlane16_swap_b32_e32 v228, v230
	v_permlane16_swap_b32_e32 v229, v231
	global_store_dwordx4 v177, v[228:231], s[24:25] offset:192
	s_cmp_lt_u32 s83, 0x1000
	s_cbranch_scc0 .Lqv_done
	global_store_dword v176, v4, s[28:29]
	global_store_dword v176, v5, s[28:29] offset:256
	global_store_dword v176, v6, s[28:29] offset:512
	global_store_dword v176, v7, s[28:29] offset:768
	global_store_dword v176, v8, s[28:29] offset:64
	global_store_dword v176, v9, s[28:29] offset:320
	global_store_dword v176, v10, s[28:29] offset:576
	global_store_dword v176, v11, s[28:29] offset:832
	global_store_dword v176, v12, s[28:29] offset:128
	global_store_dword v176, v13, s[28:29] offset:384
	global_store_dword v176, v14, s[28:29] offset:640
	global_store_dword v176, v15, s[28:29] offset:896
	global_store_dword v176, v16, s[28:29] offset:192
	global_store_dword v176, v17, s[28:29] offset:448
	global_store_dword v176, v18, s[28:29] offset:704
	global_store_dword v176, v19, s[28:29] offset:960
	v_add_u32_e32 v176, 0x1000, v176
	global_store_dword v176, v20, s[28:29]
	global_store_dword v176, v21, s[28:29] offset:256
	global_store_dword v176, v22, s[28:29] offset:512
	global_store_dword v176, v23, s[28:29] offset:768
	global_store_dword v176, v24, s[28:29] offset:64
	global_store_dword v176, v25, s[28:29] offset:320
	global_store_dword v176, v26, s[28:29] offset:576
	global_store_dword v176, v27, s[28:29] offset:832
	global_store_dword v176, v28, s[28:29] offset:128
	global_store_dword v176, v29, s[28:29] offset:384
	global_store_dword v176, v30, s[28:29] offset:640
	global_store_dword v176, v31, s[28:29] offset:896
	global_store_dword v176, v32, s[28:29] offset:192
	global_store_dword v176, v33, s[28:29] offset:448
	global_store_dword v176, v34, s[28:29] offset:704
	global_store_dword v176, v35, s[28:29] offset:960
	v_add_u32_e32 v176, 0x1000, v176
	global_store_dword v176, v36, s[28:29]
	global_store_dword v176, v37, s[28:29] offset:256
	global_store_dword v176, v38, s[28:29] offset:512
	global_store_dword v176, v39, s[28:29] offset:768
	global_store_dword v176, v40, s[28:29] offset:64
	global_store_dword v176, v41, s[28:29] offset:320
	global_store_dword v176, v42, s[28:29] offset:576
	global_store_dword v176, v43, s[28:29] offset:832
	global_store_dword v176, v44, s[28:29] offset:128
	global_store_dword v176, v45, s[28:29] offset:384
	global_store_dword v176, v46, s[28:29] offset:640
	global_store_dword v176, v47, s[28:29] offset:896
	global_store_dword v176, v48, s[28:29] offset:192
	global_store_dword v176, v49, s[28:29] offset:448
	global_store_dword v176, v50, s[28:29] offset:704
	global_store_dword v176, v51, s[28:29] offset:960
	v_add_u32_e32 v176, 0x1000, v176
	global_store_dword v176, v52, s[28:29]
	global_store_dword v176, v53, s[28:29] offset:256
	global_store_dword v176, v54, s[28:29] offset:512
	global_store_dword v176, v55, s[28:29] offset:768
	global_store_dword v176, v56, s[28:29] offset:64
	global_store_dword v176, v57, s[28:29] offset:320
	global_store_dword v176, v58, s[28:29] offset:576
	global_store_dword v176, v59, s[28:29] offset:832
	global_store_dword v176, v60, s[28:29] offset:128
	global_store_dword v176, v61, s[28:29] offset:384
	global_store_dword v176, v62, s[28:29] offset:640
	global_store_dword v176, v63, s[28:29] offset:896
	global_store_dword v176, v64, s[28:29] offset:192
	global_store_dword v176, v65, s[28:29] offset:448
	global_store_dword v176, v66, s[28:29] offset:704
	global_store_dword v176, v67, s[28:29] offset:960
	v_add_u32_e32 v176, 0x1000, v176
	global_store_dword v176, v68, s[28:29]
	global_store_dword v176, v69, s[28:29] offset:256
	global_store_dword v176, v70, s[28:29] offset:512
	global_store_dword v176, v71, s[28:29] offset:768
	global_store_dword v176, v72, s[28:29] offset:64
	global_store_dword v176, v73, s[28:29] offset:320
	global_store_dword v176, v74, s[28:29] offset:576
	global_store_dword v176, v75, s[28:29] offset:832
	global_store_dword v176, v76, s[28:29] offset:128
	global_store_dword v176, v77, s[28:29] offset:384
	global_store_dword v176, v78, s[28:29] offset:640
	global_store_dword v176, v79, s[28:29] offset:896
	global_store_dword v176, v80, s[28:29] offset:192
	global_store_dword v176, v81, s[28:29] offset:448
	global_store_dword v176, v82, s[28:29] offset:704
	global_store_dword v176, v83, s[28:29] offset:960
	v_add_u32_e32 v176, 0x1000, v176
	global_store_dword v176, v84, s[28:29]
	global_store_dword v176, v85, s[28:29] offset:256
	global_store_dword v176, v86, s[28:29] offset:512
	global_store_dword v176, v87, s[28:29] offset:768
	global_store_dword v176, v88, s[28:29] offset:64
	global_store_dword v176, v89, s[28:29] offset:320
	global_store_dword v176, v90, s[28:29] offset:576
	global_store_dword v176, v91, s[28:29] offset:832
	global_store_dword v176, v92, s[28:29] offset:128
	global_store_dword v176, v93, s[28:29] offset:384
	global_store_dword v176, v94, s[28:29] offset:640
	global_store_dword v176, v95, s[28:29] offset:896
	global_store_dword v176, v96, s[28:29] offset:192
	global_store_dword v176, v97, s[28:29] offset:448
	global_store_dword v176, v98, s[28:29] offset:704
	global_store_dword v176, v99, s[28:29] offset:960
	v_add_u32_e32 v176, 0x1000, v176
	global_store_dword v176, v100, s[28:29]
	global_store_dword v176, v101, s[28:29] offset:256
	global_store_dword v176, v102, s[28:29] offset:512
	global_store_dword v176, v103, s[28:29] offset:768
	global_store_dword v176, v104, s[28:29] offset:64
	global_store_dword v176, v105, s[28:29] offset:320
	global_store_dword v176, v106, s[28:29] offset:576
	global_store_dword v176, v107, s[28:29] offset:832
	global_store_dword v176, v108, s[28:29] offset:128
	global_store_dword v176, v109, s[28:29] offset:384
	global_store_dword v176, v110, s[28:29] offset:640
	global_store_dword v176, v111, s[28:29] offset:896
	global_store_dword v176, v112, s[28:29] offset:192
	global_store_dword v176, v113, s[28:29] offset:448
	global_store_dword v176, v114, s[28:29] offset:704
	global_store_dword v176, v115, s[28:29] offset:960
	v_add_u32_e32 v176, 0x1000, v176
	global_store_dword v176, v116, s[28:29]
	global_store_dword v176, v117, s[28:29] offset:256
	global_store_dword v176, v118, s[28:29] offset:512
	global_store_dword v176, v119, s[28:29] offset:768
	global_store_dword v176, v120, s[28:29] offset:64
	global_store_dword v176, v121, s[28:29] offset:320
	global_store_dword v176, v122, s[28:29] offset:576
	global_store_dword v176, v123, s[28:29] offset:832
	global_store_dword v176, v124, s[28:29] offset:128
	global_store_dword v176, v125, s[28:29] offset:384
	global_store_dword v176, v126, s[28:29] offset:640
	global_store_dword v176, v127, s[28:29] offset:896
	global_store_dword v176, v128, s[28:29] offset:192
	global_store_dword v176, v129, s[28:29] offset:448
	global_store_dword v176, v130, s[28:29] offset:704
	global_store_dword v176, v131, s[28:29] offset:960
.Lqv_done:
	s_nop 1
	s_branch .LBB0_305
